# fuse sub5->sub6: RES6 tiles wait on per-row-panel E_GU completion counters (deferred signals), no barrier after sub5
# baseline (speedup 1.0000x reference)
.LBB0_30:
	s_and_b32 s16, s13, -8
	s_or_b32 s41, s22, s16
	s_load_dword s16, s[96:97], 0x0
	v_readlane_b32 s17, v255, 53
	s_waitcnt lgkmcnt(0)
	s_cmp_eq_u32 s16, 0x200
	s_cbranch_scc0 .Lr6_nowait
	s_cmp_eq_u32 s17, 0
	s_cbranch_scc0 .Lr6_nowait
	v_cmp_eq_u32_e64 s[16:17], 0, v124
	s_and_saveexec_b64 s[18:19], s[16:17]
	s_cbranch_execz .Lr6_wdone
	s_lshr_b32 s16, s41, 4
	s_lshl_b32 s16, s16, 12
	s_and_b32 s17, s41, 15
	s_lshl_b32 s17, s17, 7
	s_add_i32 s16, s16, s17
	s_addk_i32 s16, 0xc00
	v_mov_b32_e32 v0, s16
	s_add_i32 s30, s12, 1
	s_mul_i32 s30, s30, 44
	s_mov_b32 s17, 0
.Lr6_spin:
	global_load_dword v1, v0, s[4:5] sc1
	s_waitcnt vmcnt(0)
	v_readfirstlane_b32 s16, v1
	s_cmp_ge_u32 s16, s30
	s_cbranch_scc1 .Lr6_wdone
	s_sleep 2
	s_add_i32 s17, s17, 1
	s_cmp_lt_u32 s17, 0x1000
	s_cbranch_scc1 .Lr6_spin
.Lr6_wdone:
	s_or_b64 exec, exec, s[18:19]
	s_barrier
.Lr6_nowait:
	s_waitcnt lgkmcnt(0)
	v_mad_i64_i32 v[0:1], s[16:17], s41, v218, v[96:97]
	s_and_b32 s16, s13, 7
	s_mul_i32 s30, s16, 0xb0000
	v_readfirstlane_b32 s16, v101
	s_mov_b32 m0, s16
	s_mov_b64 s[18:19], 0x400
	v_readfirstlane_b32 s16, v199
	global_load_lds_dwordx4 v[0:1], off
	v_lshl_add_u64 v[4:5], v[0:1], 0, s[18:19]
	s_mov_b32 m0, s16
	v_readfirstlane_b32 s16, v200
	v_lshl_add_u64 v[2:3], v[98:99], 0, s[30:31]
	global_load_lds_dwordx4 v[4:5], off
	s_mov_b32 m0, s16
	v_readfirstlane_b32 s16, v201
	global_load_lds_dwordx4 v[2:3], off
	v_lshl_add_u64 v[4:5], v[2:3], 0, s[18:19]
	s_mov_b32 m0, s16
	v_readfirstlane_b32 s16, v202
	global_load_lds_dwordx4 v[4:5], off
	v_lshl_add_u64 v[4:5], v[0:1], 0, s[44:45]
	s_mov_b32 m0, s16
	v_readfirstlane_b32 s16, v203
	global_load_lds_dwordx4 v[4:5], off
	v_lshl_add_u64 v[4:5], v[0:1], 0, s[66:67]
	s_mov_b32 m0, s16
	v_readfirstlane_b32 s16, v204
	global_load_lds_dwordx4 v[4:5], off
	v_lshl_add_u64 v[4:5], v[2:3], 0, s[44:45]
	s_mov_b32 m0, s16
	v_readfirstlane_b32 s16, v205
	global_load_lds_dwordx4 v[4:5], off
	v_lshl_add_u64 v[4:5], v[2:3], 0, s[66:67]
	s_mov_b32 m0, s16
	v_readfirstlane_b32 s16, v206
	global_load_lds_dwordx4 v[4:5], off
	v_lshl_add_u64 v[4:5], v[0:1], 0, s[28:29]
	s_mov_b32 m0, s16
	s_mov_b64 s[18:19], 0x4400
	v_readfirstlane_b32 s16, v207
	global_load_lds_dwordx4 v[4:5], off
	v_lshl_add_u64 v[0:1], v[0:1], 0, s[18:19]
	s_mov_b32 m0, s16
	v_readfirstlane_b32 s16, v208
	global_load_lds_dwordx4 v[0:1], off
	v_lshl_add_u64 v[0:1], v[2:3], 0, s[28:29]
	s_mov_b32 m0, s16
	v_readfirstlane_b32 s16, v209
	global_load_lds_dwordx4 v[0:1], off
	v_lshl_add_u64 v[0:1], v[2:3], 0, s[18:19]
	s_mov_b32 m0, s16
	s_bfe_u32 s16, s38, 0x30007
	global_load_lds_dwordx4 v[0:1], off
	v_mad_u64_u32 v[156:157], s[16:17], s16, v218, v[108:109]
	v_mad_i64_i32 v[158:159], s[16:17], s41, v218, v[110:111]
	s_lshl_b32 s16, s13, 7
	v_mov_b32_e32 v0, 0
	s_and_b32 s40, s16, 0x380
	s_mov_b32 s30, 0
	s_mov_b64 s[16:17], 0
	v_mov_b32_e32 v1, v0
	v_mov_b32_e32 v2, v0
	v_mov_b32_e32 v3, v0
	v_mov_b32_e32 v4, v0
	v_mov_b32_e32 v5, v0
	v_mov_b32_e32 v6, v0
	v_mov_b32_e32 v7, v0
	v_mov_b32_e32 v8, v0
	v_mov_b32_e32 v9, v0
	v_mov_b32_e32 v10, v0
	v_mov_b32_e32 v11, v0
	v_mov_b32_e32 v12, v0
	v_mov_b32_e32 v13, v0
	v_mov_b32_e32 v14, v0
	v_mov_b32_e32 v15, v0
	v_mov_b32_e32 v16, v0
	v_mov_b32_e32 v17, v0
	v_mov_b32_e32 v18, v0
	v_mov_b32_e32 v19, v0
	v_mov_b32_e32 v20, v0
	v_mov_b32_e32 v21, v0
	v_mov_b32_e32 v22, v0
	v_mov_b32_e32 v23, v0
	v_mov_b32_e32 v24, v0
	v_mov_b32_e32 v25, v0
	v_mov_b32_e32 v26, v0
	v_mov_b32_e32 v27, v0
	v_mov_b32_e32 v28, v0
	v_mov_b32_e32 v29, v0
	v_mov_b32_e32 v30, v0
	v_mov_b32_e32 v31, v0
	s_waitcnt vmcnt(0)
	v_mov_b32_e32 v32, v0
	v_mov_b32_e32 v33, v0
	v_mov_b32_e32 v34, v0
	v_mov_b32_e32 v35, v0
	v_mov_b32_e32 v36, v0
	v_mov_b32_e32 v37, v0
	v_mov_b32_e32 v38, v0
	v_mov_b32_e32 v39, v0
	v_mov_b32_e32 v40, v0
	v_mov_b32_e32 v41, v0
	v_mov_b32_e32 v42, v0
	v_mov_b32_e32 v43, v0
	v_mov_b32_e32 v44, v0
	v_mov_b32_e32 v45, v0
	v_mov_b32_e32 v46, v0
	v_mov_b32_e32 v47, v0
	v_mov_b32_e32 v48, v0
	v_mov_b32_e32 v49, v0
	v_mov_b32_e32 v50, v0
	v_mov_b32_e32 v51, v0
	v_mov_b32_e32 v52, v0
	v_mov_b32_e32 v53, v0
	v_mov_b32_e32 v54, v0
	v_mov_b32_e32 v55, v0
	v_mov_b32_e32 v56, v0
	v_mov_b32_e32 v57, v0
	v_mov_b32_e32 v58, v0
	v_mov_b32_e32 v59, v0
	v_mov_b32_e32 v60, v0
	v_mov_b32_e32 v61, v0
	v_mov_b32_e32 v62, v0
	v_mov_b32_e32 v63, v0
	s_branch .LBB0_32

.LBB0_116:
	s_andn2_b64 vcc, exec, s[0:1]
	s_cbranch_vccnz .LBB0_143
	s_mov_b32 s65, 0
	s_mov_b32 s63, 2
	s_mov_b32 s62, 0
	s_load_dword s0, s[96:97], 0x0
	s_and_b32 s22, s74, 7
	s_waitcnt lgkmcnt(0)
	s_lshr_b32 s13, s0, 6
	v_cvt_f32_u32_e32 v0, s13
	s_sub_i32 s1, 0, s13
	s_add_i32 s0, s13, 43
	v_rcp_iflag_f32_e32 v0, v0
	s_nop 0
	v_mul_f32_e32 v0, 0x4f7ffffe, v0
	v_cvt_u32_f32_e32 v0, v0
	s_nop 0
	v_readfirstlane_b32 s8, v0
	s_mul_i32 s1, s1, s8
	s_mul_hi_u32 s1, s8, s1
	s_add_i32 s8, s8, s1
	s_mul_hi_u32 s1, s0, s8
	s_mul_i32 s8, s1, s13
	s_sub_i32 s0, s0, s8
	s_add_i32 s9, s1, 1
	s_sub_i32 s8, s0, s13
	s_cmp_ge_u32 s0, s13
	s_cselect_b32 s1, s9, s1
	s_cselect_b32 s0, s8, s0
	s_add_i32 s8, s1, 1
	s_cmp_ge_u32 s0, s13
	s_cselect_b32 s23, s8, s1
	s_mul_i32 s23, s23, 6
	s_cmp_ge_u32 s22, s23
	s_cbranch_scc1 .LBB0_143
	s_cmp_eq_u32 s13, 8
	s_cbranch_scc0 .Lgu_orig1
	s_mov_b32 s63, 0
	s_lshr_b32 s22, s74, 3
	s_movk_i32 s23, 0x88
	s_mov_b64 s[8:9], 0
	s_cmp_lt_u32 s22, 0x80
	s_cbranch_scc0 .Ldec_s1
	s_mul_hi_u32 s1, s22, 0x2aaaaaab
	s_mul_i32 s15, s1, 6
	s_sub_i32 s15, s22, s15
	s_lshl_b32 s1, s1, 1
	s_branch .Ldec_e1

.Lgu_ein:
	v_cvt_f32_i32_e32 v87, v69
	ds_read_b128 v[108:111], v106
	ds_read_b128 v[112:115], v106 offset:32
	ds_read_b128 v[128:131], v106 offset:64
	ds_read_b128 v[132:135], v106 offset:96
	ds_read_b128 v[76:79], v106 offset:128
	ds_read_b128 v[72:75], v106 offset:160
	v_cvt_f32_i32_e32 v119, v68
	ds_read_b128 v[68:71], v106 offset:192
	ds_read_b128 v[64:67], v106 offset:224
	v_mul_f32_e32 v87, 0x33800000, v87
	s_waitcnt lgkmcnt(0)
	v_fma_f32 v48, v48, v108, v87
	v_fma_f32 v49, v49, v109, v87
	v_fma_f32 v50, v50, v110, v87
	v_fma_f32 v51, v51, v111, v87
	v_fma_f32 v52, v52, v112, v87
	v_fma_f32 v53, v53, v113, v87
	v_fma_f32 v54, v54, v114, v87
	v_fma_f32 v55, v55, v115, v87
	v_fma_f32 v56, v56, v128, v87
	v_fma_f32 v57, v57, v129, v87
	v_fma_f32 v58, v58, v130, v87
	v_fma_f32 v59, v59, v131, v87
	v_fma_f32 v60, v60, v132, v87
	v_fma_f32 v61, v61, v133, v87
	v_fma_f32 v62, v62, v134, v87
	v_fma_f32 v63, v63, v135, v87
	v_mul_f32_e32 v119, 0x33800000, v119
	v_mul_f32_e32 v121, 0xbfb8aa3b, v48
	v_mul_f32_e32 v122, 0xbfb8aa3b, v49
	v_mul_f32_e32 v125, 0xbfb8aa3b, v50
	v_mul_f32_e32 v136, 0xbfb8aa3b, v51
	v_mul_f32_e32 v137, 0xbfb8aa3b, v52
	v_mul_f32_e32 v138, 0xbfb8aa3b, v53
	v_mul_f32_e32 v139, 0xbfb8aa3b, v54
	v_mul_f32_e32 v140, 0xbfb8aa3b, v55
	v_mul_f32_e32 v141, 0xbfb8aa3b, v56
	v_mul_f32_e32 v142, 0xbfb8aa3b, v57
	v_mul_f32_e32 v143, 0xbfb8aa3b, v58
	v_mul_f32_e32 v144, 0xbfb8aa3b, v59
	v_mul_f32_e32 v145, 0xbfb8aa3b, v60
	v_mul_f32_e32 v146, 0xbfb8aa3b, v61
	v_mul_f32_e32 v147, 0xbfb8aa3b, v62
	v_mul_f32_e32 v148, 0xbfb8aa3b, v63
	v_exp_f32_e32 v121, v121
	v_exp_f32_e32 v122, v122
	v_exp_f32_e32 v125, v125
	v_exp_f32_e32 v136, v136
	v_exp_f32_e32 v137, v137
	v_exp_f32_e32 v138, v138
	v_exp_f32_e32 v139, v139
	v_exp_f32_e32 v140, v140
	v_exp_f32_e32 v141, v141
	v_exp_f32_e32 v142, v142
	v_exp_f32_e32 v143, v143
	v_exp_f32_e32 v144, v144
	v_exp_f32_e32 v145, v145
	v_exp_f32_e32 v146, v146
	v_exp_f32_e32 v147, v147
	v_exp_f32_e32 v148, v148
	v_add_f32_e32 v121, 1.0, v121
	v_add_f32_e32 v122, 1.0, v122
	v_add_f32_e32 v125, 1.0, v125
	v_add_f32_e32 v136, 1.0, v136
	v_add_f32_e32 v137, 1.0, v137
	v_add_f32_e32 v138, 1.0, v138
	v_add_f32_e32 v139, 1.0, v139
	v_add_f32_e32 v140, 1.0, v140
	v_add_f32_e32 v141, 1.0, v141
	v_add_f32_e32 v142, 1.0, v142
	v_add_f32_e32 v143, 1.0, v143
	v_add_f32_e32 v144, 1.0, v144
	v_add_f32_e32 v145, 1.0, v145
	v_add_f32_e32 v146, 1.0, v146
	v_add_f32_e32 v147, 1.0, v147
	v_add_f32_e32 v148, 1.0, v148
	v_rcp_f32_e32 v121, v121
	v_rcp_f32_e32 v122, v122
	v_rcp_f32_e32 v125, v125
	v_rcp_f32_e32 v136, v136
	v_rcp_f32_e32 v137, v137
	v_rcp_f32_e32 v138, v138
	v_rcp_f32_e32 v139, v139
	v_rcp_f32_e32 v140, v140
	v_rcp_f32_e32 v141, v141
	v_rcp_f32_e32 v142, v142
	v_rcp_f32_e32 v143, v143
	v_rcp_f32_e32 v144, v144
	v_rcp_f32_e32 v145, v145
	v_rcp_f32_e32 v146, v146
	v_rcp_f32_e32 v147, v147
	v_rcp_f32_e32 v148, v148
	v_mul_f32_e32 v48, v48, v121
	v_fma_f32 v32, v32, v108, v119
	v_mul_f32_e32 v32, v32, v48
	v_mul_f32_e32 v48, v49, v122
	v_fma_f32 v33, v33, v109, v119
	v_mul_f32_e32 v33, v33, v48
	v_mul_f32_e32 v48, v50, v125
	v_fma_f32 v34, v34, v110, v119
	v_cvt_pk_bf16_f32 v32, v32, s0
	v_mul_f32_e32 v34, v34, v48
	v_mul_f32_e32 v48, v51, v136
	v_fma_f32 v35, v35, v111, v119
	ds_write_b16 v107, v32 offset:49152
	v_cvt_pk_bf16_f32 v32, v33, s0
	v_mul_f32_e32 v35, v35, v48
	v_mul_f32_e32 v48, v52, v137
	v_fma_f32 v36, v36, v112, v119
	ds_write_b16 v107, v32 offset:49296
	v_cvt_pk_bf16_f32 v32, v34, s0
	v_mul_f32_e32 v36, v36, v48
	v_mul_f32_e32 v48, v53, v138
	v_fma_f32 v37, v37, v113, v119
	ds_write_b16 v107, v32 offset:49440
	v_cvt_pk_bf16_f32 v32, v35, s0
	v_mul_f32_e32 v37, v37, v48
	v_mul_f32_e32 v48, v54, v139
	v_fma_f32 v38, v38, v114, v119
	ds_write_b16 v107, v32 offset:49584
	v_cvt_pk_bf16_f32 v32, v36, s0
	v_mul_f32_e32 v38, v38, v48
	v_mul_f32_e32 v48, v55, v140
	v_fma_f32 v39, v39, v115, v119
	ds_write_b16 v107, v32 offset:50304
	v_cvt_pk_bf16_f32 v32, v37, s0
	v_mul_f32_e32 v39, v39, v48
	v_mul_f32_e32 v48, v56, v141
	v_fma_f32 v40, v40, v128, v119
	ds_write_b16 v107, v32 offset:50448
	v_cvt_pk_bf16_f32 v32, v38, s0
	v_mul_f32_e32 v40, v40, v48
	v_mul_f32_e32 v48, v57, v142
	v_fma_f32 v41, v41, v129, v119
	ds_write_b16 v107, v32 offset:50592
	v_cvt_pk_bf16_f32 v32, v39, s0
	v_mul_f32_e32 v41, v41, v48
	v_mul_f32_e32 v48, v58, v143
	v_fma_f32 v42, v42, v130, v119
	ds_write_b16 v107, v32 offset:50736
	v_cvt_pk_bf16_f32 v32, v40, s0
	v_mul_f32_e32 v42, v42, v48
	v_mul_f32_e32 v48, v59, v144
	v_fma_f32 v43, v43, v131, v119
	ds_write_b16 v107, v32 offset:51456
	v_cvt_pk_bf16_f32 v32, v41, s0
	v_mul_f32_e32 v43, v43, v48
	v_mul_f32_e32 v48, v60, v145
	v_fma_f32 v44, v44, v132, v119
	ds_write_b16 v107, v32 offset:51600
	v_cvt_pk_bf16_f32 v32, v42, s0
	v_mul_f32_e32 v44, v44, v48
	v_mul_f32_e32 v48, v61, v146
	v_fma_f32 v45, v45, v133, v119
	ds_write_b16 v107, v32 offset:51744
	v_cvt_pk_bf16_f32 v32, v43, s0
	v_mul_f32_e32 v45, v45, v48
	v_mul_f32_e32 v48, v62, v147
	v_fma_f32 v46, v46, v134, v119
	ds_write_b16 v107, v32 offset:51888
	v_cvt_pk_bf16_f32 v32, v44, s0
	v_mul_f32_e32 v46, v46, v48
	v_mul_f32_e32 v48, v63, v148
	v_fma_f32 v47, v47, v135, v119
	ds_write_b16 v107, v32 offset:52608
	v_cvt_pk_bf16_f32 v32, v45, s0
	v_mul_f32_e32 v47, v47, v48
	ds_write_b16 v107, v32 offset:52752
	v_cvt_pk_bf16_f32 v32, v46, s0
	ds_write_b16 v107, v32 offset:52896
	v_cvt_pk_bf16_f32 v32, v47, s0
	v_fma_f32 v16, v16, v76, v87
	v_fma_f32 v17, v17, v77, v87
	v_fma_f32 v18, v18, v78, v87
	v_fma_f32 v19, v19, v79, v87
	v_fma_f32 v20, v20, v72, v87
	v_fma_f32 v21, v21, v73, v87
	v_fma_f32 v22, v22, v74, v87
	v_fma_f32 v23, v23, v75, v87
	v_fma_f32 v24, v24, v68, v87
	v_fma_f32 v25, v25, v69, v87
	v_fma_f32 v26, v26, v70, v87
	v_fma_f32 v27, v27, v71, v87
	v_fma_f32 v28, v28, v64, v87
	v_fma_f32 v29, v29, v65, v87
	v_fma_f32 v30, v30, v66, v87
	v_fmac_f32_e32 v87, v31, v67
	ds_write_b16 v107, v32 offset:53040
	v_mul_f32_e32 v31, 0xbfb8aa3b, v16
	v_mul_f32_e32 v32, 0xbfb8aa3b, v17
	v_mul_f32_e32 v33, 0xbfb8aa3b, v18
	v_mul_f32_e32 v34, 0xbfb8aa3b, v19
	v_mul_f32_e32 v35, 0xbfb8aa3b, v20
	v_mul_f32_e32 v36, 0xbfb8aa3b, v21
	v_mul_f32_e32 v37, 0xbfb8aa3b, v22
	v_mul_f32_e32 v38, 0xbfb8aa3b, v23
	v_mul_f32_e32 v39, 0xbfb8aa3b, v24
	v_mul_f32_e32 v40, 0xbfb8aa3b, v25
	v_mul_f32_e32 v41, 0xbfb8aa3b, v26
	v_mul_f32_e32 v42, 0xbfb8aa3b, v27
	v_mul_f32_e32 v43, 0xbfb8aa3b, v28
	v_mul_f32_e32 v44, 0xbfb8aa3b, v29
	v_mul_f32_e32 v45, 0xbfb8aa3b, v30
	v_mul_f32_e32 v46, 0xbfb8aa3b, v87
	v_exp_f32_e32 v31, v31
	v_exp_f32_e32 v32, v32
	v_exp_f32_e32 v33, v33
	v_exp_f32_e32 v34, v34
	v_exp_f32_e32 v35, v35
	v_exp_f32_e32 v36, v36
	v_exp_f32_e32 v37, v37
	v_exp_f32_e32 v38, v38
	v_exp_f32_e32 v39, v39
	v_exp_f32_e32 v40, v40
	v_exp_f32_e32 v41, v41
	v_exp_f32_e32 v42, v42
	v_exp_f32_e32 v43, v43
	v_exp_f32_e32 v44, v44
	v_exp_f32_e32 v45, v45
	v_exp_f32_e32 v46, v46
	v_add_f32_e32 v31, 1.0, v31
	v_add_f32_e32 v32, 1.0, v32
	v_add_f32_e32 v33, 1.0, v33
	v_add_f32_e32 v34, 1.0, v34
	v_add_f32_e32 v35, 1.0, v35
	v_add_f32_e32 v36, 1.0, v36
	v_add_f32_e32 v37, 1.0, v37
	v_add_f32_e32 v38, 1.0, v38
	v_add_f32_e32 v39, 1.0, v39
	v_add_f32_e32 v40, 1.0, v40
	v_add_f32_e32 v41, 1.0, v41
	v_add_f32_e32 v42, 1.0, v42
	v_add_f32_e32 v43, 1.0, v43
	v_add_f32_e32 v44, 1.0, v44
	v_add_f32_e32 v45, 1.0, v45
	v_add_f32_e32 v46, 1.0, v46
	v_rcp_f32_e32 v31, v31
	v_rcp_f32_e32 v32, v32
	v_rcp_f32_e32 v33, v33
	v_rcp_f32_e32 v34, v34
	v_rcp_f32_e32 v35, v35
	v_rcp_f32_e32 v36, v36
	v_rcp_f32_e32 v37, v37
	v_rcp_f32_e32 v38, v38
	v_rcp_f32_e32 v39, v39
	v_rcp_f32_e32 v40, v40
	v_rcp_f32_e32 v41, v41
	v_rcp_f32_e32 v42, v42
	v_rcp_f32_e32 v43, v43
	v_rcp_f32_e32 v44, v44
	v_rcp_f32_e32 v45, v45
	v_rcp_f32_e32 v46, v46
	v_mul_f32_e32 v16, v16, v31
	v_fma_f32 v0, v0, v76, v119
	v_mul_f32_e32 v0, v0, v16
	v_mul_f32_e32 v16, v17, v32
	v_fma_f32 v1, v1, v77, v119
	v_mul_f32_e32 v1, v1, v16
	v_mul_f32_e32 v16, v18, v33
	v_fma_f32 v2, v2, v78, v119
	v_cvt_pk_bf16_f32 v0, v0, s0
	v_mul_f32_e32 v2, v2, v16
	v_mul_f32_e32 v16, v19, v34
	v_fma_f32 v3, v3, v79, v119
	ds_write_b16 v107, v0 offset:53760
	v_cvt_pk_bf16_f32 v0, v1, s0
	v_mul_f32_e32 v3, v3, v16
	v_mul_f32_e32 v16, v20, v35
	v_fma_f32 v4, v4, v72, v119
	ds_write_b16 v107, v0 offset:53904
	v_cvt_pk_bf16_f32 v0, v2, s0
	v_mul_f32_e32 v4, v4, v16
	v_mul_f32_e32 v16, v21, v36
	v_fma_f32 v5, v5, v73, v119
	ds_write_b16 v107, v0 offset:54048
	v_cvt_pk_bf16_f32 v0, v3, s0
	v_mul_f32_e32 v5, v5, v16
	v_mul_f32_e32 v16, v22, v37
	v_fma_f32 v6, v6, v74, v119
	ds_write_b16 v107, v0 offset:54192
	v_cvt_pk_bf16_f32 v0, v4, s0
	v_mul_f32_e32 v6, v6, v16
	v_mul_f32_e32 v16, v23, v38
	v_fma_f32 v7, v7, v75, v119
	ds_write_b16 v107, v0 offset:54912
	v_cvt_pk_bf16_f32 v0, v5, s0
	v_mul_f32_e32 v7, v7, v16
	v_mul_f32_e32 v16, v24, v39
	v_fma_f32 v8, v8, v68, v119
	ds_write_b16 v107, v0 offset:55056
	v_cvt_pk_bf16_f32 v0, v6, s0
	v_mul_f32_e32 v8, v8, v16
	v_mul_f32_e32 v16, v25, v40
	v_fma_f32 v9, v9, v69, v119
	ds_write_b16 v107, v0 offset:55200
	v_cvt_pk_bf16_f32 v0, v7, s0
	v_mul_f32_e32 v9, v9, v16
	v_mul_f32_e32 v16, v26, v41
	v_fma_f32 v10, v10, v70, v119
	ds_write_b16 v107, v0 offset:55344
	v_cvt_pk_bf16_f32 v0, v8, s0
	v_mul_f32_e32 v10, v10, v16
	v_mul_f32_e32 v16, v27, v42
	v_fma_f32 v11, v11, v71, v119
	ds_write_b16 v107, v0 offset:56064
	v_cvt_pk_bf16_f32 v0, v9, s0
	v_mul_f32_e32 v11, v11, v16
	v_mul_f32_e32 v16, v28, v43
	v_fma_f32 v12, v12, v64, v119
	ds_write_b16 v107, v0 offset:56208
	v_cvt_pk_bf16_f32 v0, v10, s0
	v_mul_f32_e32 v12, v12, v16
	v_mul_f32_e32 v16, v29, v44
	v_fma_f32 v13, v13, v65, v119
	ds_write_b16 v107, v0 offset:56352
	v_cvt_pk_bf16_f32 v0, v11, s0
	v_mul_f32_e32 v13, v13, v16
	v_mul_f32_e32 v16, v30, v45
	v_fma_f32 v14, v14, v66, v119
	ds_write_b16 v107, v0 offset:56496
	v_cvt_pk_bf16_f32 v0, v12, s0
	v_mul_f32_e32 v14, v14, v16
	v_mul_f32_e32 v16, v87, v46
	v_fmac_f32_e32 v119, v15, v67
	ds_write_b16 v107, v0 offset:57216
	v_cvt_pk_bf16_f32 v0, v13, s0
	v_mul_f32_e32 v15, v119, v16
	ds_write_b16 v107, v0 offset:57360
	v_cvt_pk_bf16_f32 v0, v14, s0
	ds_write_b16 v107, v0 offset:57504
	v_cvt_pk_bf16_f32 v0, v15, s0
	v_add_u32_e32 v4, s0, v94
	s_ashr_i32 s1, s14, 1
	ds_write_b16 v107, v0 offset:57648
	v_add_u32_e32 v5, s1, v95
	v_ashrrev_i32_e32 v0, 7, v4
	s_movk_i32 s14, 0x58
	v_mul_lo_u32 v0, v0, s14
	v_ashrrev_i32_e32 v2, 5, v5
	v_ashrrev_i32_e32 v1, 31, v0
	v_ashrrev_i32_e32 v3, 31, v2
	v_lshl_add_u64 v[0:1], v[0:1], 0, v[2:3]
	v_lshlrev_b64 v[0:1], 13, v[0:1]
	v_lshlrev_b32_e32 v2, 6, v4
	v_and_b32_e32 v5, 31, v5
	v_lshl_add_u64 v[0:1], s[8:9], 0, v[0:1]
	v_and_b32_e32 v2, 0x1fc0, v2
	v_mov_b32_e32 v3, v117
	v_lshl_add_u64 v[0:1], v[0:1], 0, v[2:3]
	v_lshlrev_b32_e32 v2, 1, v5
	s_waitcnt lgkmcnt(0)
	s_barrier
	v_lshl_add_u64 v[4:5], v[0:1], 0, v[2:3]
	ds_read_b128 v[0:3], v96 offset:49152
	s_mov_b64 s[18:19], -1
	s_and_b64 vcc, exec, s[10:11]
	s_waitcnt lgkmcnt(0)
	global_store_dwordx4 v[4:5], v[0:3], off
	v_add_u32_e32 v4, s0, v97
	v_add_u32_e32 v5, s1, v98
	v_ashrrev_i32_e32 v0, 7, v4
	v_mul_lo_u32 v0, v0, s14
	v_ashrrev_i32_e32 v2, 5, v5
	v_ashrrev_i32_e32 v1, 31, v0
	v_ashrrev_i32_e32 v3, 31, v2
	v_lshl_add_u64 v[0:1], v[0:1], 0, v[2:3]
	v_lshlrev_b64 v[0:1], 13, v[0:1]
	v_lshlrev_b32_e32 v2, 6, v4
	v_and_b32_e32 v5, 31, v5
	v_lshl_add_u64 v[0:1], s[8:9], 0, v[0:1]
	v_and_b32_e32 v2, 0x1fc0, v2
	v_mov_b32_e32 v3, v117
	v_lshl_add_u64 v[0:1], v[0:1], 0, v[2:3]
	v_lshlrev_b32_e32 v2, 1, v5
	v_lshl_add_u64 v[4:5], v[0:1], 0, v[2:3]
	ds_read_b128 v[0:3], v99 offset:49152
	s_waitcnt lgkmcnt(0)
	global_store_dwordx4 v[4:5], v[0:3], off
	v_add_u32_e32 v4, s0, v100
	v_add_u32_e32 v5, s1, v101
	v_ashrrev_i32_e32 v0, 7, v4
	v_mul_lo_u32 v0, v0, s14
	v_ashrrev_i32_e32 v2, 5, v5
	v_ashrrev_i32_e32 v1, 31, v0
	v_ashrrev_i32_e32 v3, 31, v2
	v_lshl_add_u64 v[0:1], v[0:1], 0, v[2:3]
	v_lshlrev_b64 v[0:1], 13, v[0:1]
	v_lshlrev_b32_e32 v2, 6, v4
	v_and_b32_e32 v5, 31, v5
	v_lshl_add_u64 v[0:1], s[8:9], 0, v[0:1]
	v_and_b32_e32 v2, 0x1fc0, v2
	v_mov_b32_e32 v3, v117
	v_lshl_add_u64 v[0:1], v[0:1], 0, v[2:3]
	v_lshlrev_b32_e32 v2, 1, v5
	v_lshl_add_u64 v[4:5], v[0:1], 0, v[2:3]
	ds_read_b128 v[0:3], v102 offset:49152
	s_waitcnt lgkmcnt(0)
	global_store_dwordx4 v[4:5], v[0:3], off
	v_add_u32_e32 v4, s0, v103
	v_add_u32_e32 v5, s1, v104
	v_ashrrev_i32_e32 v0, 7, v4
	v_mul_lo_u32 v0, v0, s14
	v_ashrrev_i32_e32 v2, 5, v5
	v_ashrrev_i32_e32 v1, 31, v0
	v_ashrrev_i32_e32 v3, 31, v2
	v_lshl_add_u64 v[0:1], v[0:1], 0, v[2:3]
	v_lshlrev_b64 v[0:1], 13, v[0:1]
	v_lshlrev_b32_e32 v2, 6, v4
	v_and_b32_e32 v5, 31, v5
	v_lshl_add_u64 v[0:1], s[8:9], 0, v[0:1]
	v_and_b32_e32 v2, 0x1fc0, v2
	v_mov_b32_e32 v3, v117
	v_lshl_add_u64 v[0:1], v[0:1], 0, v[2:3]
	v_lshlrev_b32_e32 v2, 1, v5
	v_lshl_add_u64 v[4:5], v[0:1], 0, v[2:3]
	ds_read_b128 v[0:3], v105 offset:49152
	s_lshr_b32 s64, s0, 7
	s_mov_b32 s14, s35
	s_mov_b32 s0, s38
	s_waitcnt lgkmcnt(0)
	global_store_dwordx4 v[4:5], v[0:3], off
	s_waitcnt lgkmcnt(0)
	s_barrier
	s_add_i32 s65, s65, 1
	s_cmp_eq_u32 s62, 2
	s_cbranch_scc0 .Lgu_eout
	s_mov_b32 s62, 0
	s_mov_b32 s38, s60
	s_mov_b32 s35, s61
	v_mov_b32_e32 v48, v150
	v_mov_b32_e32 v49, v151
	v_mov_b32_e32 v50, v152
	v_mov_b32_e32 v51, v153
	v_mov_b32_e32 v52, v154
	v_mov_b32_e32 v53, v155
	v_mov_b32_e32 v54, v156
	v_mov_b32_e32 v55, v157
	v_mov_b32_e32 v56, v158
	v_mov_b32_e32 v57, v159
	v_mov_b32_e32 v58, v160
	v_mov_b32_e32 v59, v161
	v_mov_b32_e32 v60, v162
	v_mov_b32_e32 v61, v163
	v_mov_b32_e32 v62, v164
	v_mov_b32_e32 v63, v165
	v_mov_b32_e32 v32, v166
	v_mov_b32_e32 v33, v167
	v_mov_b32_e32 v34, v168
	v_mov_b32_e32 v35, v169
	v_mov_b32_e32 v36, v170
	v_mov_b32_e32 v37, v171
	v_mov_b32_e32 v38, v172
	v_mov_b32_e32 v39, v173
	v_mov_b32_e32 v40, v174
	v_mov_b32_e32 v41, v175
	v_mov_b32_e32 v42, v176
	v_mov_b32_e32 v43, v177
	v_mov_b32_e32 v44, v178
	v_mov_b32_e32 v45, v179
	v_mov_b32_e32 v46, v180
	v_mov_b32_e32 v47, v181
	v_mov_b32_e32 v16, v184
	v_mov_b32_e32 v17, v185
	v_mov_b32_e32 v18, v186
	v_mov_b32_e32 v19, v187
	v_mov_b32_e32 v20, v188
	v_mov_b32_e32 v21, v189
	v_mov_b32_e32 v22, v190
	v_mov_b32_e32 v23, v191
	v_mov_b32_e32 v24, v192
	v_mov_b32_e32 v25, v193
	v_mov_b32_e32 v26, v194
	v_mov_b32_e32 v27, v195
	v_mov_b32_e32 v28, v196
	v_mov_b32_e32 v29, v197
	v_mov_b32_e32 v30, v198
	v_mov_b32_e32 v31, v199
	v_mov_b32_e32 v0, v226
	v_mov_b32_e32 v1, v227
	v_mov_b32_e32 v2, v228
	v_mov_b32_e32 v3, v229
	v_mov_b32_e32 v4, v230
	v_mov_b32_e32 v5, v231
	v_mov_b32_e32 v6, v232
	v_mov_b32_e32 v7, v233
	v_mov_b32_e32 v8, v234
	v_mov_b32_e32 v9, v235
	v_mov_b32_e32 v10, v236
	v_mov_b32_e32 v11, v237
	v_mov_b32_e32 v12, v238
	v_mov_b32_e32 v13, v239
	v_mov_b32_e32 v14, v240
	v_mov_b32_e32 v15, v241
	v_mov_b32_e32 v69, v201
	v_mov_b32_e32 v68, v200
	s_branch .LBB0_126
.Lgu_eout:
	s_cbranch_vccz .Lgu_more
	s_waitcnt vmcnt(0)
	s_barrier
	s_cmp_eq_u32 s65, 0
	s_cbranch_scc1 .Lgf_2
	v_cmp_eq_u32_e64 s[70:71], 0, v124
	s_and_saveexec_b64 s[68:69], s[70:71]
	s_cbranch_execz .Lgf_2x
	s_lshr_b32 s70, s64, 4
	s_lshl_b32 s70, s70, 12
	s_and_b32 s71, s64, 15
	s_lshl_b32 s71, s71, 7
	s_add_i32 s70, s70, s71
	s_addk_i32 s70, 0xc00
	v_mov_b32_e32 v0, s70
	v_mov_b32_e32 v1, s65
	global_atomic_add v0, v1, s[4:5]
.Lgf_2x:
	s_or_b64 exec, exec, s[68:69]
	s_mov_b32 s65, 0

.Lgu_more:
.LBB0_127:
	s_mov_b64 s[16:17], 0
	s_cmp_ge_i32 s22, s23
	s_cbranch_scc0 .LBB0_139

.LBB0_136:
	s_or_b64 exec, exec, s[18:19]
	s_waitcnt lgkmcnt(0)
	s_andn2_b64 vcc, exec, s[16:17]
	s_mov_b64 s[66:67], 0x2400
	s_barrier
	s_cmp_eq_u32 s65, 0
	s_cbranch_scc1 .Lgf_1
	v_cmp_eq_u32_e64 s[70:71], 0, v124
	s_and_saveexec_b64 s[68:69], s[70:71]
	s_cbranch_execz .Lgf_1x
	s_lshr_b32 s70, s64, 4
	s_lshl_b32 s70, s70, 12
	s_and_b32 s71, s64, 15
	s_lshl_b32 s71, s71, 7
	s_add_i32 s70, s70, s71
	s_addk_i32 s70, 0xc00
	v_mov_b32_e32 v128, s70
	v_mov_b32_e32 v129, s65
	global_atomic_add v128, v129, s[4:5]

.Lgf_1:
	s_cbranch_vccnz .LBB0_126
	s_ashr_i32 s16, s38, 7
	s_ashr_i32 s17, s16, 31
	s_lshl_b64 s[16:17], s[16:17], 18
	v_lshl_add_u64 v[64:65], v[80:81], 0, s[16:17]
	s_ashr_i32 s16, s35, 7
	s_ashr_i32 s17, s16, 31
	s_lshl_b64 s[16:17], s[16:17], 18
	v_readfirstlane_b32 s1, v88
	v_lshl_add_u64 v[66:67], v[82:83], 0, s[16:17]
	s_mov_b64 s[16:17], 0x400
	s_mov_b32 m0, s1
	v_readfirstlane_b32 s1, v108
	v_lshl_add_u64 v[110:111], v[64:65], 0, s[16:17]
	global_load_lds_dwordx4 v[64:65], off
	s_mov_b32 m0, s1
	v_readfirstlane_b32 s1, v87
	global_load_lds_dwordx4 v[110:111], off
	s_mov_b32 m0, s1
	v_readfirstlane_b32 s1, v79
	global_load_lds_dwordx4 v[66:67], off
	v_lshl_add_u64 v[108:109], v[66:67], 0, s[16:17]
	s_mov_b32 m0, s1
	v_readfirstlane_b32 s1, v78
	global_load_lds_dwordx4 v[108:109], off
	v_lshl_add_u64 v[108:109], v[64:65], 0, s[44:45]
	s_mov_b32 m0, s1
	v_readfirstlane_b32 s1, v77
	global_load_lds_dwordx4 v[108:109], off
	v_lshl_add_u64 v[78:79], v[64:65], 0, s[66:67]
	s_mov_b32 m0, s1
	v_readfirstlane_b32 s1, v76
	global_load_lds_dwordx4 v[78:79], off
	v_lshl_add_u64 v[78:79], v[66:67], 0, s[44:45]
	s_mov_b32 m0, s1
	v_readfirstlane_b32 s1, v75
	global_load_lds_dwordx4 v[78:79], off
	v_lshl_add_u64 v[76:77], v[66:67], 0, s[66:67]
	s_mov_b32 m0, s1
	v_readfirstlane_b32 s1, v74
	global_load_lds_dwordx4 v[76:77], off
	v_lshl_add_u64 v[76:77], v[64:65], 0, s[28:29]
	s_mov_b32 m0, s1
	s_mov_b64 s[16:17], 0x4400
	v_readfirstlane_b32 s1, v73
	global_load_lds_dwordx4 v[76:77], off
	v_lshl_add_u64 v[64:65], v[64:65], 0, s[16:17]
	s_mov_b32 m0, s1
	v_readfirstlane_b32 s1, v71
	global_load_lds_dwordx4 v[64:65], off
	v_lshl_add_u64 v[64:65], v[66:67], 0, s[28:29]
	s_mov_b32 m0, s1
	v_readfirstlane_b32 s1, v70
	global_load_lds_dwordx4 v[64:65], off
	v_lshl_add_u64 v[64:65], v[66:67], 0, s[16:17]
	s_mov_b32 m0, s1
	s_nop 0
	global_load_lds_dwordx4 v[64:65], off
	s_branch .LBB0_126

.Llb_chk:
	s_cmp_eq_u32 s99, 2
	s_cbranch_scc1 .Llb_do
	s_cmp_eq_u32 s99, 4
	s_cbranch_scc1 .Llb_do
	s_cmp_eq_u32 s99, 5
	s_cbranch_scc0 .LBB0_509
	s_waitcnt vmcnt(0) lgkmcnt(0)
	s_barrier
	s_mov_b64 s[0:1], 0
	s_branch .Llong21
